# peer_ffn rewritten by hand: 8 column-slice sweeps of the fp8 up table, y slices staged in out (f32), LDS transpose-reduce, then per-wave residual+LayerNorm with DPP reductions
# speedup vs baseline: 1.0899x; 1.0350x over previous
; DI void phase_peer_ffn(const Params& p) {
;   const char* exu = p.ws + OFF_EXU;
;   const float* h = (const float*)(p.ws + OFF_H);
;   const int* eidx = (const int*)(p.ws + OFF_EIDX);
;   const float* coefw = (const float*)(p.ws + OFF_COEF);
;   const int lane = threadIdx.x & 63;
;   const int gw = (blockIdx.x * blockDim.x + threadIdx.x) >> 6;
;   const int nw = (gridDim.x * blockDim.x) >> 6;
;   for (int tok = gw; tok < T_; tok += nw) {
;     float yacc[16];
; #pragma unroll
;     for (int i = 0; i < 16; ++i) yacc[i] = 0.f;
;     const int e_lo = eidx[(size_t)tok * 128 + lane];
;     const int e_hi = eidx[(size_t)tok * 128 + 64 + lane];
;     const float c_lo = coefw[(size_t)tok * 128 + lane];
;     const float c_hi = coefw[(size_t)tok * 128 + 64 + lane];
; #pragma unroll 1
;     for (int eb = 0; eb < 8; ++eb) {
;       const int ev = (eb < 4) ? e_lo : e_hi;
;       const float cv = (eb < 4) ? c_lo : c_hi;
;       const int lbase = (eb & 3) * 16;
;       u32x4 ur[16];
; #pragma unroll
;       for (int k = 0; k < 16; ++k) {
;         const int er = __builtin_amdgcn_readlane(ev, lbase + k);
;         ur[k] = *reinterpret_cast<const u32x4*>(exu + (size_t)er * 1024 + lane * 16);
;       }
.LBB0_1085:
	s_or_b64 exec, exec, s[4:5]
	s_waitcnt lgkmcnt(0)
	s_barrier
	s_and_saveexec_b64 s[4:5], s[2:3]
	s_cbranch_execz .LBB0_1090
	s_mov_b32 s2, s96
	s_mov_b32 s3, s97
	s_add_u32 s6, s96, 0x5000000
	s_addc_u32 s7, s97, 0
	s_add_u32 s8, s96, 0x2000000
	s_addc_u32 s9, s97, 0
	v_mbcnt_lo_u32_b32 v0, -1, 0
	v_mbcnt_hi_u32_b32 v0, -1, v0
	v_lshrrev_b32_e32 v1, 3, v0
	v_and_b32_e32 v2, 7, v0
	v_lshlrev_b32_e32 v2, 4, v2
	v_lshl_add_u32 v3, v1, 9, v2
	v_lshlrev_b32_e32 v1, 2, v1
	v_lshlrev_b32_e32 v4, 3, v0
	v_and_b32_e32 v5, 7, v64
	v_lshlrev_b32_e32 v5, 12, v5
	v_add_u32_e32 v3, v5, v3
	v_add_u32_e32 v4, v5, v4
	v_and_b32_e32 v5, 14, v0
	v_lshlrev_b32_e32 v5, 5, v5
	v_lshrrev_b32_e32 v6, 4, v0
	v_lshl_add_u32 v5, v6, 4, v5
	v_and_b32_e32 v6, 1, v0
	v_lshl_add_u32 v5, v6, 3, v5
	v_lshl_add_u32 v9, v64, 9, v1
	global_load_dword v100, v9, s[2:3] offset:0
	global_load_dword v101, v9, s[2:3] offset:32
	global_load_dword v102, v9, s[2:3] offset:64
	global_load_dword v103, v9, s[2:3] offset:96
	global_load_dword v104, v9, s[2:3] offset:128
	global_load_dword v105, v9, s[2:3] offset:160
	global_load_dword v106, v9, s[2:3] offset:192
	global_load_dword v107, v9, s[2:3] offset:224
	global_load_dword v108, v9, s[2:3] offset:256
	global_load_dword v109, v9, s[2:3] offset:288
	global_load_dword v110, v9, s[2:3] offset:320
	global_load_dword v111, v9, s[2:3] offset:352
	global_load_dword v112, v9, s[2:3] offset:384
	global_load_dword v113, v9, s[2:3] offset:416
	global_load_dword v114, v9, s[2:3] offset:448
	global_load_dword v115, v9, s[2:3] offset:480
	global_load_dword v132, v9, s[8:9] offset:0
	global_load_dword v133, v9, s[8:9] offset:32
	global_load_dword v134, v9, s[8:9] offset:64
	global_load_dword v135, v9, s[8:9] offset:96
	global_load_dword v136, v9, s[8:9] offset:128
	global_load_dword v137, v9, s[8:9] offset:160
	global_load_dword v138, v9, s[8:9] offset:192
	global_load_dword v139, v9, s[8:9] offset:224
	global_load_dword v140, v9, s[8:9] offset:256
	global_load_dword v141, v9, s[8:9] offset:288
	global_load_dword v142, v9, s[8:9] offset:320
	global_load_dword v143, v9, s[8:9] offset:352
	global_load_dword v144, v9, s[8:9] offset:384
	global_load_dword v145, v9, s[8:9] offset:416
	global_load_dword v146, v9, s[8:9] offset:448
	global_load_dword v147, v9, s[8:9] offset:480
	v_add_u32_e32 v6, 0x800, v64
	v_lshl_add_u32 v9, v6, 9, v1
	global_load_dword v116, v9, s[2:3] offset:0
	global_load_dword v117, v9, s[2:3] offset:32
	global_load_dword v118, v9, s[2:3] offset:64
	global_load_dword v119, v9, s[2:3] offset:96
	global_load_dword v120, v9, s[2:3] offset:128
	global_load_dword v121, v9, s[2:3] offset:160
	global_load_dword v122, v9, s[2:3] offset:192
	global_load_dword v123, v9, s[2:3] offset:224
	global_load_dword v124, v9, s[2:3] offset:256
	global_load_dword v125, v9, s[2:3] offset:288
	global_load_dword v126, v9, s[2:3] offset:320
	global_load_dword v127, v9, s[2:3] offset:352
	global_load_dword v128, v9, s[2:3] offset:384
	global_load_dword v129, v9, s[2:3] offset:416
	global_load_dword v130, v9, s[2:3] offset:448
	global_load_dword v131, v9, s[2:3] offset:480
	s_waitcnt vmcnt(32)
	v_lshl_add_u32 v11, v100, 10, v2
	global_load_dwordx4 v[180:183], v11, s[6:7]
	v_lshl_add_u32 v11, v101, 10, v2
	global_load_dwordx4 v[184:187], v11, s[6:7]
	v_lshl_add_u32 v11, v102, 10, v2
	global_load_dwordx4 v[188:191], v11, s[6:7]
	v_lshl_add_u32 v11, v103, 10, v2
	global_load_dwordx4 v[192:195], v11, s[6:7]
	v_lshl_add_u32 v11, v104, 10, v2
	global_load_dwordx4 v[196:199], v11, s[6:7]
	v_lshl_add_u32 v11, v105, 10, v2
	global_load_dwordx4 v[200:203], v11, s[6:7]
	v_lshl_add_u32 v11, v106, 10, v2
	global_load_dwordx4 v[204:207], v11, s[6:7]
	v_lshl_add_u32 v11, v107, 10, v2
	global_load_dwordx4 v[208:211], v11, s[6:7]
	v_lshl_add_u32 v11, v108, 10, v2
	global_load_dwordx4 v[212:215], v11, s[6:7]
	v_lshl_add_u32 v11, v109, 10, v2
	global_load_dwordx4 v[216:219], v11, s[6:7]
	v_lshl_add_u32 v11, v110, 10, v2
	global_load_dwordx4 v[220:223], v11, s[6:7]
	v_lshl_add_u32 v11, v111, 10, v2
	global_load_dwordx4 v[224:227], v11, s[6:7]
	v_lshl_add_u32 v11, v112, 10, v2
	global_load_dwordx4 v[228:231], v11, s[6:7]
	v_lshl_add_u32 v11, v113, 10, v2
	global_load_dwordx4 v[232:235], v11, s[6:7]
	v_lshl_add_u32 v11, v114, 10, v2
	global_load_dwordx4 v[236:239], v11, s[6:7]
	v_lshl_add_u32 v11, v115, 10, v2
	global_load_dwordx4 v[240:243], v11, s[6:7]
	v_lshl_add_u32 v12, v64, 12, v5
	global_store_dwordx2 v12, v[82:83], s[58:59]
	s_mov_b32 s18, 0
; DI void phase_peer_ffn(const Params& p) {
;     ...
; #pragma unroll 1
;     for (int eb = 0; eb < 8; ++eb) {
;       const int ev = (eb < 4) ? e_lo : e_hi;
;       const float cv = (eb < 4) ? c_lo : c_hi;
;       const int lbase = (eb & 3) * 16;
;       u32x4 ur[16];
; #pragma unroll
;       for (int k = 0; k < 16; ++k) {
;         const int er = __builtin_amdgcn_readlane(ev, lbase + k);
;         ur[k] = *reinterpret_cast<const u32x4*>(exu + (size_t)er * 1024 + lane * 16);
;       }
; #pragma unroll
;       for (int k = 0; k < 16; ++k) {
;         const float ck = __int_as_float(__builtin_amdgcn_readlane(__float_as_int(cv), lbase + k));
; #pragma unroll
;         for (int w = 0; w < 4; ++w) {
;           f2_t lo = __builtin_amdgcn_cvt_pk_f32_fp8((int)ur[k][w], false);
;           f2_t hi = __builtin_amdgcn_cvt_pk_f32_fp8((int)ur[k][w], true);
;           yacc[4 * w] = fmaf(ck, lo[0], yacc[4 * w]);
;           yacc[4 * w + 1] = fmaf(ck, lo[1], yacc[4 * w + 1]);
;           yacc[4 * w + 2] = fmaf(ck, hi[0], yacc[4 * w + 2]);
;           yacc[4 * w + 3] = fmaf(ck, hi[1], yacc[4 * w + 3]);
;         }
;       }
.Lpf_loop:
	s_add_i32 s20, s18, 1
	s_min_i32 s20, s20, 0x7f
	s_lshr_b32 s21, s20, 4
	s_and_b32 s22, s20, 15
	s_add_i32 s23, s18, 2
	s_min_i32 s23, s23, 0x7f
	s_and_b32 s24, s23, 15
	s_and_b32 s26, s18, 15
	s_lshr_b32 s27, s18, 4
	s_lshl_b32 s22, s22, 11
	s_lshl_b32 s24, s24, 11
	s_lshl_b32 s28, s21, 7
	s_lshl_b32 s26, s26, 11
	s_lshl_b32 s27, s27, 9
	v_add_u32_e32 v6, s22, v64
	v_add_u32_e32 v7, s24, v64
	v_add_u32_e32 v8, s28, v2
	v_lshl_add_u32 v10, v6, 9, v1
	v_lshl_add_u32 v9, v7, 9, v1
	v_add_u32_e32 v12, s26, v64
	v_lshl_add_u32 v12, v12, 12, v5
	v_add_u32_e32 v12, s27, v12
	s_waitcnt vmcnt(17)
	global_load_dword v100, v9, s[2:3] offset:0
	global_load_dword v101, v9, s[2:3] offset:32
	global_load_dword v102, v9, s[2:3] offset:64
	global_load_dword v103, v9, s[2:3] offset:96
	global_load_dword v104, v9, s[2:3] offset:128
	global_load_dword v105, v9, s[2:3] offset:160
	global_load_dword v106, v9, s[2:3] offset:192
	global_load_dword v107, v9, s[2:3] offset:224
	global_load_dword v108, v9, s[2:3] offset:256
	global_load_dword v109, v9, s[2:3] offset:288
	global_load_dword v110, v9, s[2:3] offset:320
	global_load_dword v111, v9, s[2:3] offset:352
	global_load_dword v112, v9, s[2:3] offset:384
	global_load_dword v113, v9, s[2:3] offset:416
	global_load_dword v114, v9, s[2:3] offset:448
	global_load_dword v115, v9, s[2:3] offset:480
	global_load_dword v36, v10, s[8:9] offset:0
	global_load_dword v37, v10, s[8:9] offset:32
	global_load_dword v38, v10, s[8:9] offset:64
	global_load_dword v39, v10, s[8:9] offset:96
	global_load_dword v40, v10, s[8:9] offset:128
	global_load_dword v41, v10, s[8:9] offset:160
	global_load_dword v42, v10, s[8:9] offset:192
	global_load_dword v43, v10, s[8:9] offset:224
	global_load_dword v244, v10, s[8:9] offset:256
	global_load_dword v245, v10, s[8:9] offset:288
	global_load_dword v246, v10, s[8:9] offset:320
	global_load_dword v247, v10, s[8:9] offset:352
	global_load_dword v248, v10, s[8:9] offset:384
	global_load_dword v249, v10, s[8:9] offset:416
	global_load_dword v250, v10, s[8:9] offset:448
	global_load_dword v251, v10, s[8:9] offset:480
	s_waitcnt vmcnt(47)
	v_cvt_pk_f32_fp8_e32 v[44:45], v180
	v_cvt_pk_f32_fp8_sdwa v[46:47], v180 src0_sel:WORD_1
	v_cvt_pk_f32_fp8_e32 v[48:49], v181
	v_cvt_pk_f32_fp8_sdwa v[50:51], v181 src0_sel:WORD_1
	v_cvt_pk_f32_fp8_e32 v[52:53], v182
	v_cvt_pk_f32_fp8_sdwa v[54:55], v182 src0_sel:WORD_1
	v_cvt_pk_f32_fp8_e32 v[56:57], v183
	v_cvt_pk_f32_fp8_sdwa v[58:59], v183 src0_sel:WORD_1
	v_cvt_pk_f32_fp8_e32 v[66:67], v184
	v_cvt_pk_f32_fp8_sdwa v[68:69], v184 src0_sel:WORD_1
	v_cvt_pk_f32_fp8_e32 v[70:71], v185
	v_cvt_pk_f32_fp8_sdwa v[72:73], v185 src0_sel:WORD_1
	v_cvt_pk_f32_fp8_e32 v[74:75], v186
	v_cvt_pk_f32_fp8_sdwa v[76:77], v186 src0_sel:WORD_1
	v_cvt_pk_f32_fp8_e32 v[78:79], v187
	v_cvt_pk_f32_fp8_sdwa v[80:81], v187 src0_sel:WORD_1
	v_lshl_add_u32 v11, v116, 10, v8
	v_lshl_add_u32 v65, v117, 10, v8
	global_load_dwordx4 v[180:183], v11, s[6:7]
	global_load_dwordx4 v[184:187], v65, s[6:7]
	v_pk_mul_f32 v[20:21], v[44:45], v[132:133] op_sel_hi:[1,0]
	v_pk_mul_f32 v[22:23], v[46:47], v[132:133] op_sel_hi:[1,0]
	v_pk_mul_f32 v[24:25], v[48:49], v[132:133] op_sel_hi:[1,0]
	v_pk_mul_f32 v[26:27], v[50:51], v[132:133] op_sel_hi:[1,0]
	v_pk_mul_f32 v[28:29], v[52:53], v[132:133] op_sel_hi:[1,0]
	v_pk_mul_f32 v[30:31], v[54:55], v[132:133] op_sel_hi:[1,0]
	v_pk_mul_f32 v[32:33], v[56:57], v[132:133] op_sel_hi:[1,0]
	v_pk_mul_f32 v[34:35], v[58:59], v[132:133] op_sel_hi:[1,0]
	v_pk_fma_f32 v[20:21], v[66:67], v[132:133], v[20:21] op_sel:[0,1,0]
	v_pk_fma_f32 v[22:23], v[68:69], v[132:133], v[22:23] op_sel:[0,1,0]
	v_pk_fma_f32 v[24:25], v[70:71], v[132:133], v[24:25] op_sel:[0,1,0]
	v_pk_fma_f32 v[26:27], v[72:73], v[132:133], v[26:27] op_sel:[0,1,0]
	v_pk_fma_f32 v[28:29], v[74:75], v[132:133], v[28:29] op_sel:[0,1,0]
	v_pk_fma_f32 v[30:31], v[76:77], v[132:133], v[30:31] op_sel:[0,1,0]
	v_pk_fma_f32 v[32:33], v[78:79], v[132:133], v[32:33] op_sel:[0,1,0]
	v_pk_fma_f32 v[34:35], v[80:81], v[132:133], v[34:35] op_sel:[0,1,0]
	s_waitcnt vmcnt(47)
	v_cvt_pk_f32_fp8_e32 v[44:45], v188
	v_cvt_pk_f32_fp8_sdwa v[46:47], v188 src0_sel:WORD_1
	v_cvt_pk_f32_fp8_e32 v[48:49], v189
	v_cvt_pk_f32_fp8_sdwa v[50:51], v189 src0_sel:WORD_1
	v_cvt_pk_f32_fp8_e32 v[52:53], v190
	v_cvt_pk_f32_fp8_sdwa v[54:55], v190 src0_sel:WORD_1
	v_cvt_pk_f32_fp8_e32 v[56:57], v191
	v_cvt_pk_f32_fp8_sdwa v[58:59], v191 src0_sel:WORD_1
	v_cvt_pk_f32_fp8_e32 v[66:67], v192
	v_cvt_pk_f32_fp8_sdwa v[68:69], v192 src0_sel:WORD_1
	v_cvt_pk_f32_fp8_e32 v[70:71], v193
	v_cvt_pk_f32_fp8_sdwa v[72:73], v193 src0_sel:WORD_1
	v_cvt_pk_f32_fp8_e32 v[74:75], v194
	v_cvt_pk_f32_fp8_sdwa v[76:77], v194 src0_sel:WORD_1
	v_cvt_pk_f32_fp8_e32 v[78:79], v195
	v_cvt_pk_f32_fp8_sdwa v[80:81], v195 src0_sel:WORD_1
	v_lshl_add_u32 v11, v118, 10, v8
	v_lshl_add_u32 v65, v119, 10, v8
	global_load_dwordx4 v[188:191], v11, s[6:7]
	global_load_dwordx4 v[192:195], v65, s[6:7]
	v_pk_fma_f32 v[20:21], v[44:45], v[134:135], v[20:21] op_sel_hi:[1,0,1]
	v_pk_fma_f32 v[22:23], v[46:47], v[134:135], v[22:23] op_sel_hi:[1,0,1]
	v_pk_fma_f32 v[24:25], v[48:49], v[134:135], v[24:25] op_sel_hi:[1,0,1]
	v_pk_fma_f32 v[26:27], v[50:51], v[134:135], v[26:27] op_sel_hi:[1,0,1]
	v_pk_fma_f32 v[28:29], v[52:53], v[134:135], v[28:29] op_sel_hi:[1,0,1]
	v_pk_fma_f32 v[30:31], v[54:55], v[134:135], v[30:31] op_sel_hi:[1,0,1]
	v_pk_fma_f32 v[32:33], v[56:57], v[134:135], v[32:33] op_sel_hi:[1,0,1]
	v_pk_fma_f32 v[34:35], v[58:59], v[134:135], v[34:35] op_sel_hi:[1,0,1]
	v_pk_fma_f32 v[20:21], v[66:67], v[134:135], v[20:21] op_sel:[0,1,0]
	v_pk_fma_f32 v[22:23], v[68:69], v[134:135], v[22:23] op_sel:[0,1,0]
	v_pk_fma_f32 v[24:25], v[70:71], v[134:135], v[24:25] op_sel:[0,1,0]
	v_pk_fma_f32 v[26:27], v[72:73], v[134:135], v[26:27] op_sel:[0,1,0]
	v_pk_fma_f32 v[28:29], v[74:75], v[134:135], v[28:29] op_sel:[0,1,0]
	v_pk_fma_f32 v[30:31], v[76:77], v[134:135], v[30:31] op_sel:[0,1,0]
	v_pk_fma_f32 v[32:33], v[78:79], v[134:135], v[32:33] op_sel:[0,1,0]
	v_pk_fma_f32 v[34:35], v[80:81], v[134:135], v[34:35] op_sel:[0,1,0]
	s_waitcnt vmcnt(47)
; DI void phase_peer_ffn(const Params& p) {
;     ...
; #pragma unroll
;       for (int k = 0; k < 16; ++k) {
;         const float ck = __int_as_float(__builtin_amdgcn_readlane(__float_as_int(cv), lbase + k));
; #pragma unroll
;         for (int w = 0; w < 4; ++w) {
;           f2_t lo = __builtin_amdgcn_cvt_pk_f32_fp8((int)ur[k][w], false);
;           f2_t hi = __builtin_amdgcn_cvt_pk_f32_fp8((int)ur[k][w], true);
;           yacc[4 * w] = fmaf(ck, lo[0], yacc[4 * w]);
;           yacc[4 * w + 1] = fmaf(ck, lo[1], yacc[4 * w + 1]);
;           yacc[4 * w + 2] = fmaf(ck, hi[0], yacc[4 * w + 2]);
;           yacc[4 * w + 3] = fmaf(ck, hi[1], yacc[4 * w + 3]);
;         }
;       }
	v_cvt_pk_f32_fp8_e32 v[44:45], v196
	v_cvt_pk_f32_fp8_sdwa v[46:47], v196 src0_sel:WORD_1
	v_cvt_pk_f32_fp8_e32 v[48:49], v197
	v_cvt_pk_f32_fp8_sdwa v[50:51], v197 src0_sel:WORD_1
	v_cvt_pk_f32_fp8_e32 v[52:53], v198
	v_cvt_pk_f32_fp8_sdwa v[54:55], v198 src0_sel:WORD_1
	v_cvt_pk_f32_fp8_e32 v[56:57], v199
	v_cvt_pk_f32_fp8_sdwa v[58:59], v199 src0_sel:WORD_1
	v_cvt_pk_f32_fp8_e32 v[66:67], v200
	v_cvt_pk_f32_fp8_sdwa v[68:69], v200 src0_sel:WORD_1
	v_cvt_pk_f32_fp8_e32 v[70:71], v201
	v_cvt_pk_f32_fp8_sdwa v[72:73], v201 src0_sel:WORD_1
	v_cvt_pk_f32_fp8_e32 v[74:75], v202
	v_cvt_pk_f32_fp8_sdwa v[76:77], v202 src0_sel:WORD_1
	v_cvt_pk_f32_fp8_e32 v[78:79], v203
	v_cvt_pk_f32_fp8_sdwa v[80:81], v203 src0_sel:WORD_1
	v_lshl_add_u32 v11, v120, 10, v8
	v_lshl_add_u32 v65, v121, 10, v8
	global_load_dwordx4 v[196:199], v11, s[6:7]
	global_load_dwordx4 v[200:203], v65, s[6:7]
	v_pk_fma_f32 v[20:21], v[44:45], v[136:137], v[20:21] op_sel_hi:[1,0,1]
	v_pk_fma_f32 v[22:23], v[46:47], v[136:137], v[22:23] op_sel_hi:[1,0,1]
	v_pk_fma_f32 v[24:25], v[48:49], v[136:137], v[24:25] op_sel_hi:[1,0,1]
	v_pk_fma_f32 v[26:27], v[50:51], v[136:137], v[26:27] op_sel_hi:[1,0,1]
	v_pk_fma_f32 v[28:29], v[52:53], v[136:137], v[28:29] op_sel_hi:[1,0,1]
	v_pk_fma_f32 v[30:31], v[54:55], v[136:137], v[30:31] op_sel_hi:[1,0,1]
	v_pk_fma_f32 v[32:33], v[56:57], v[136:137], v[32:33] op_sel_hi:[1,0,1]
	v_pk_fma_f32 v[34:35], v[58:59], v[136:137], v[34:35] op_sel_hi:[1,0,1]
	v_pk_fma_f32 v[20:21], v[66:67], v[136:137], v[20:21] op_sel:[0,1,0]
	v_pk_fma_f32 v[22:23], v[68:69], v[136:137], v[22:23] op_sel:[0,1,0]
	v_pk_fma_f32 v[24:25], v[70:71], v[136:137], v[24:25] op_sel:[0,1,0]
	v_pk_fma_f32 v[26:27], v[72:73], v[136:137], v[26:27] op_sel:[0,1,0]
	v_pk_fma_f32 v[28:29], v[74:75], v[136:137], v[28:29] op_sel:[0,1,0]
	v_pk_fma_f32 v[30:31], v[76:77], v[136:137], v[30:31] op_sel:[0,1,0]
	v_pk_fma_f32 v[32:33], v[78:79], v[136:137], v[32:33] op_sel:[0,1,0]
	v_pk_fma_f32 v[34:35], v[80:81], v[136:137], v[34:35] op_sel:[0,1,0]
	s_waitcnt vmcnt(47)
	v_cvt_pk_f32_fp8_e32 v[44:45], v204
	v_cvt_pk_f32_fp8_sdwa v[46:47], v204 src0_sel:WORD_1
	v_cvt_pk_f32_fp8_e32 v[48:49], v205
	v_cvt_pk_f32_fp8_sdwa v[50:51], v205 src0_sel:WORD_1
	v_cvt_pk_f32_fp8_e32 v[52:53], v206
	v_cvt_pk_f32_fp8_sdwa v[54:55], v206 src0_sel:WORD_1
	v_cvt_pk_f32_fp8_e32 v[56:57], v207
	v_cvt_pk_f32_fp8_sdwa v[58:59], v207 src0_sel:WORD_1
	v_cvt_pk_f32_fp8_e32 v[66:67], v208
	v_cvt_pk_f32_fp8_sdwa v[68:69], v208 src0_sel:WORD_1
	v_cvt_pk_f32_fp8_e32 v[70:71], v209
	v_cvt_pk_f32_fp8_sdwa v[72:73], v209 src0_sel:WORD_1
	v_cvt_pk_f32_fp8_e32 v[74:75], v210
	v_cvt_pk_f32_fp8_sdwa v[76:77], v210 src0_sel:WORD_1
	v_cvt_pk_f32_fp8_e32 v[78:79], v211
	v_cvt_pk_f32_fp8_sdwa v[80:81], v211 src0_sel:WORD_1
	v_lshl_add_u32 v11, v122, 10, v8
	v_lshl_add_u32 v65, v123, 10, v8
	global_load_dwordx4 v[204:207], v11, s[6:7]
	global_load_dwordx4 v[208:211], v65, s[6:7]
	v_pk_fma_f32 v[20:21], v[44:45], v[138:139], v[20:21] op_sel_hi:[1,0,1]
	v_pk_fma_f32 v[22:23], v[46:47], v[138:139], v[22:23] op_sel_hi:[1,0,1]
	v_pk_fma_f32 v[24:25], v[48:49], v[138:139], v[24:25] op_sel_hi:[1,0,1]
	v_pk_fma_f32 v[26:27], v[50:51], v[138:139], v[26:27] op_sel_hi:[1,0,1]
	v_pk_fma_f32 v[28:29], v[52:53], v[138:139], v[28:29] op_sel_hi:[1,0,1]
	v_pk_fma_f32 v[30:31], v[54:55], v[138:139], v[30:31] op_sel_hi:[1,0,1]
	v_pk_fma_f32 v[32:33], v[56:57], v[138:139], v[32:33] op_sel_hi:[1,0,1]
	v_pk_fma_f32 v[34:35], v[58:59], v[138:139], v[34:35] op_sel_hi:[1,0,1]
	v_pk_fma_f32 v[20:21], v[66:67], v[138:139], v[20:21] op_sel:[0,1,0]
	v_pk_fma_f32 v[22:23], v[68:69], v[138:139], v[22:23] op_sel:[0,1,0]
	v_pk_fma_f32 v[24:25], v[70:71], v[138:139], v[24:25] op_sel:[0,1,0]
	v_pk_fma_f32 v[26:27], v[72:73], v[138:139], v[26:27] op_sel:[0,1,0]
	v_pk_fma_f32 v[28:29], v[74:75], v[138:139], v[28:29] op_sel:[0,1,0]
	v_pk_fma_f32 v[30:31], v[76:77], v[138:139], v[30:31] op_sel:[0,1,0]
	v_pk_fma_f32 v[32:33], v[78:79], v[138:139], v[32:33] op_sel:[0,1,0]
	v_pk_fma_f32 v[34:35], v[80:81], v[138:139], v[34:35] op_sel:[0,1,0]
	s_waitcnt vmcnt(47)
	v_cvt_pk_f32_fp8_e32 v[44:45], v212
	v_cvt_pk_f32_fp8_sdwa v[46:47], v212 src0_sel:WORD_1
	v_cvt_pk_f32_fp8_e32 v[48:49], v213
	v_cvt_pk_f32_fp8_sdwa v[50:51], v213 src0_sel:WORD_1
	v_cvt_pk_f32_fp8_e32 v[52:53], v214
	v_cvt_pk_f32_fp8_sdwa v[54:55], v214 src0_sel:WORD_1
	v_cvt_pk_f32_fp8_e32 v[56:57], v215
	v_cvt_pk_f32_fp8_sdwa v[58:59], v215 src0_sel:WORD_1
	v_cvt_pk_f32_fp8_e32 v[66:67], v216
	v_cvt_pk_f32_fp8_sdwa v[68:69], v216 src0_sel:WORD_1
	v_cvt_pk_f32_fp8_e32 v[70:71], v217
	v_cvt_pk_f32_fp8_sdwa v[72:73], v217 src0_sel:WORD_1
	v_cvt_pk_f32_fp8_e32 v[74:75], v218
	v_cvt_pk_f32_fp8_sdwa v[76:77], v218 src0_sel:WORD_1
	v_cvt_pk_f32_fp8_e32 v[78:79], v219
	v_cvt_pk_f32_fp8_sdwa v[80:81], v219 src0_sel:WORD_1
	v_lshl_add_u32 v11, v124, 10, v8
	v_lshl_add_u32 v65, v125, 10, v8
	global_load_dwordx4 v[212:215], v11, s[6:7]
	global_load_dwordx4 v[216:219], v65, s[6:7]
	v_pk_fma_f32 v[20:21], v[44:45], v[140:141], v[20:21] op_sel_hi:[1,0,1]
	v_pk_fma_f32 v[22:23], v[46:47], v[140:141], v[22:23] op_sel_hi:[1,0,1]
	v_pk_fma_f32 v[24:25], v[48:49], v[140:141], v[24:25] op_sel_hi:[1,0,1]
	v_pk_fma_f32 v[26:27], v[50:51], v[140:141], v[26:27] op_sel_hi:[1,0,1]
	v_pk_fma_f32 v[28:29], v[52:53], v[140:141], v[28:29] op_sel_hi:[1,0,1]
	v_pk_fma_f32 v[30:31], v[54:55], v[140:141], v[30:31] op_sel_hi:[1,0,1]
	v_pk_fma_f32 v[32:33], v[56:57], v[140:141], v[32:33] op_sel_hi:[1,0,1]
	v_pk_fma_f32 v[34:35], v[58:59], v[140:141], v[34:35] op_sel_hi:[1,0,1]
	v_pk_fma_f32 v[20:21], v[66:67], v[140:141], v[20:21] op_sel:[0,1,0]
	v_pk_fma_f32 v[22:23], v[68:69], v[140:141], v[22:23] op_sel:[0,1,0]
	v_pk_fma_f32 v[24:25], v[70:71], v[140:141], v[24:25] op_sel:[0,1,0]
	v_pk_fma_f32 v[26:27], v[72:73], v[140:141], v[26:27] op_sel:[0,1,0]
	v_pk_fma_f32 v[28:29], v[74:75], v[140:141], v[28:29] op_sel:[0,1,0]
	v_pk_fma_f32 v[30:31], v[76:77], v[140:141], v[30:31] op_sel:[0,1,0]
	v_pk_fma_f32 v[32:33], v[78:79], v[140:141], v[32:33] op_sel:[0,1,0]
	v_pk_fma_f32 v[34:35], v[80:81], v[140:141], v[34:35] op_sel:[0,1,0]
	s_waitcnt vmcnt(47)
; DI void phase_peer_ffn(const Params& p) {
;     ...
; #pragma unroll
;       for (int k = 0; k < 16; ++k) {
;         const float ck = __int_as_float(__builtin_amdgcn_readlane(__float_as_int(cv), lbase + k));
; #pragma unroll
;         for (int w = 0; w < 4; ++w) {
;           f2_t lo = __builtin_amdgcn_cvt_pk_f32_fp8((int)ur[k][w], false);
;           f2_t hi = __builtin_amdgcn_cvt_pk_f32_fp8((int)ur[k][w], true);
;           yacc[4 * w] = fmaf(ck, lo[0], yacc[4 * w]);
;           yacc[4 * w + 1] = fmaf(ck, lo[1], yacc[4 * w + 1]);
;           yacc[4 * w + 2] = fmaf(ck, hi[0], yacc[4 * w + 2]);
;           yacc[4 * w + 3] = fmaf(ck, hi[1], yacc[4 * w + 3]);
;         }
;       }
	v_cvt_pk_f32_fp8_e32 v[44:45], v220
	v_cvt_pk_f32_fp8_sdwa v[46:47], v220 src0_sel:WORD_1
	v_cvt_pk_f32_fp8_e32 v[48:49], v221
	v_cvt_pk_f32_fp8_sdwa v[50:51], v221 src0_sel:WORD_1
	v_cvt_pk_f32_fp8_e32 v[52:53], v222
	v_cvt_pk_f32_fp8_sdwa v[54:55], v222 src0_sel:WORD_1
	v_cvt_pk_f32_fp8_e32 v[56:57], v223
	v_cvt_pk_f32_fp8_sdwa v[58:59], v223 src0_sel:WORD_1
	v_cvt_pk_f32_fp8_e32 v[66:67], v224
	v_cvt_pk_f32_fp8_sdwa v[68:69], v224 src0_sel:WORD_1
	v_cvt_pk_f32_fp8_e32 v[70:71], v225
	v_cvt_pk_f32_fp8_sdwa v[72:73], v225 src0_sel:WORD_1
	v_cvt_pk_f32_fp8_e32 v[74:75], v226
	v_cvt_pk_f32_fp8_sdwa v[76:77], v226 src0_sel:WORD_1
	v_cvt_pk_f32_fp8_e32 v[78:79], v227
	v_cvt_pk_f32_fp8_sdwa v[80:81], v227 src0_sel:WORD_1
	v_lshl_add_u32 v11, v126, 10, v8
	v_lshl_add_u32 v65, v127, 10, v8
	global_load_dwordx4 v[220:223], v11, s[6:7]
	global_load_dwordx4 v[224:227], v65, s[6:7]
	v_pk_fma_f32 v[20:21], v[44:45], v[142:143], v[20:21] op_sel_hi:[1,0,1]
	v_pk_fma_f32 v[22:23], v[46:47], v[142:143], v[22:23] op_sel_hi:[1,0,1]
	v_pk_fma_f32 v[24:25], v[48:49], v[142:143], v[24:25] op_sel_hi:[1,0,1]
	v_pk_fma_f32 v[26:27], v[50:51], v[142:143], v[26:27] op_sel_hi:[1,0,1]
	v_pk_fma_f32 v[28:29], v[52:53], v[142:143], v[28:29] op_sel_hi:[1,0,1]
	v_pk_fma_f32 v[30:31], v[54:55], v[142:143], v[30:31] op_sel_hi:[1,0,1]
	v_pk_fma_f32 v[32:33], v[56:57], v[142:143], v[32:33] op_sel_hi:[1,0,1]
	v_pk_fma_f32 v[34:35], v[58:59], v[142:143], v[34:35] op_sel_hi:[1,0,1]
	v_pk_fma_f32 v[20:21], v[66:67], v[142:143], v[20:21] op_sel:[0,1,0]
	v_pk_fma_f32 v[22:23], v[68:69], v[142:143], v[22:23] op_sel:[0,1,0]
	v_pk_fma_f32 v[24:25], v[70:71], v[142:143], v[24:25] op_sel:[0,1,0]
	v_pk_fma_f32 v[26:27], v[72:73], v[142:143], v[26:27] op_sel:[0,1,0]
	v_pk_fma_f32 v[28:29], v[74:75], v[142:143], v[28:29] op_sel:[0,1,0]
	v_pk_fma_f32 v[30:31], v[76:77], v[142:143], v[30:31] op_sel:[0,1,0]
	v_pk_fma_f32 v[32:33], v[78:79], v[142:143], v[32:33] op_sel:[0,1,0]
	v_pk_fma_f32 v[34:35], v[80:81], v[142:143], v[34:35] op_sel:[0,1,0]
	s_waitcnt vmcnt(47)
	v_cvt_pk_f32_fp8_e32 v[44:45], v228
	v_cvt_pk_f32_fp8_sdwa v[46:47], v228 src0_sel:WORD_1
	v_cvt_pk_f32_fp8_e32 v[48:49], v229
	v_cvt_pk_f32_fp8_sdwa v[50:51], v229 src0_sel:WORD_1
	v_cvt_pk_f32_fp8_e32 v[52:53], v230
	v_cvt_pk_f32_fp8_sdwa v[54:55], v230 src0_sel:WORD_1
	v_cvt_pk_f32_fp8_e32 v[56:57], v231
	v_cvt_pk_f32_fp8_sdwa v[58:59], v231 src0_sel:WORD_1
	v_cvt_pk_f32_fp8_e32 v[66:67], v232
	v_cvt_pk_f32_fp8_sdwa v[68:69], v232 src0_sel:WORD_1
	v_cvt_pk_f32_fp8_e32 v[70:71], v233
	v_cvt_pk_f32_fp8_sdwa v[72:73], v233 src0_sel:WORD_1
	v_cvt_pk_f32_fp8_e32 v[74:75], v234
	v_cvt_pk_f32_fp8_sdwa v[76:77], v234 src0_sel:WORD_1
	v_cvt_pk_f32_fp8_e32 v[78:79], v235
	v_cvt_pk_f32_fp8_sdwa v[80:81], v235 src0_sel:WORD_1
	v_lshl_add_u32 v11, v128, 10, v8
	v_lshl_add_u32 v65, v129, 10, v8
	global_load_dwordx4 v[228:231], v11, s[6:7]
	global_load_dwordx4 v[232:235], v65, s[6:7]
	v_pk_fma_f32 v[20:21], v[44:45], v[144:145], v[20:21] op_sel_hi:[1,0,1]
	v_pk_fma_f32 v[22:23], v[46:47], v[144:145], v[22:23] op_sel_hi:[1,0,1]
	v_pk_fma_f32 v[24:25], v[48:49], v[144:145], v[24:25] op_sel_hi:[1,0,1]
	v_pk_fma_f32 v[26:27], v[50:51], v[144:145], v[26:27] op_sel_hi:[1,0,1]
	v_pk_fma_f32 v[28:29], v[52:53], v[144:145], v[28:29] op_sel_hi:[1,0,1]
	v_pk_fma_f32 v[30:31], v[54:55], v[144:145], v[30:31] op_sel_hi:[1,0,1]
	v_pk_fma_f32 v[32:33], v[56:57], v[144:145], v[32:33] op_sel_hi:[1,0,1]
	v_pk_fma_f32 v[34:35], v[58:59], v[144:145], v[34:35] op_sel_hi:[1,0,1]
	v_pk_fma_f32 v[20:21], v[66:67], v[144:145], v[20:21] op_sel:[0,1,0]
	v_pk_fma_f32 v[22:23], v[68:69], v[144:145], v[22:23] op_sel:[0,1,0]
	v_pk_fma_f32 v[24:25], v[70:71], v[144:145], v[24:25] op_sel:[0,1,0]
	v_pk_fma_f32 v[26:27], v[72:73], v[144:145], v[26:27] op_sel:[0,1,0]
	v_pk_fma_f32 v[28:29], v[74:75], v[144:145], v[28:29] op_sel:[0,1,0]
	v_pk_fma_f32 v[30:31], v[76:77], v[144:145], v[30:31] op_sel:[0,1,0]
	v_pk_fma_f32 v[32:33], v[78:79], v[144:145], v[32:33] op_sel:[0,1,0]
	v_pk_fma_f32 v[34:35], v[80:81], v[144:145], v[34:35] op_sel:[0,1,0]
	s_waitcnt vmcnt(47)
	v_cvt_pk_f32_fp8_e32 v[44:45], v236
	v_cvt_pk_f32_fp8_sdwa v[46:47], v236 src0_sel:WORD_1
	v_cvt_pk_f32_fp8_e32 v[48:49], v237
	v_cvt_pk_f32_fp8_sdwa v[50:51], v237 src0_sel:WORD_1
	v_cvt_pk_f32_fp8_e32 v[52:53], v238
	v_cvt_pk_f32_fp8_sdwa v[54:55], v238 src0_sel:WORD_1
	v_cvt_pk_f32_fp8_e32 v[56:57], v239
	v_cvt_pk_f32_fp8_sdwa v[58:59], v239 src0_sel:WORD_1
	v_cvt_pk_f32_fp8_e32 v[66:67], v240
	v_cvt_pk_f32_fp8_sdwa v[68:69], v240 src0_sel:WORD_1
	v_cvt_pk_f32_fp8_e32 v[70:71], v241
	v_cvt_pk_f32_fp8_sdwa v[72:73], v241 src0_sel:WORD_1
	v_cvt_pk_f32_fp8_e32 v[74:75], v242
	v_cvt_pk_f32_fp8_sdwa v[76:77], v242 src0_sel:WORD_1
	v_cvt_pk_f32_fp8_e32 v[78:79], v243
	v_cvt_pk_f32_fp8_sdwa v[80:81], v243 src0_sel:WORD_1
	v_lshl_add_u32 v11, v130, 10, v8
	v_lshl_add_u32 v65, v131, 10, v8
	global_load_dwordx4 v[236:239], v11, s[6:7]
	global_load_dwordx4 v[240:243], v65, s[6:7]
	v_pk_fma_f32 v[20:21], v[44:45], v[146:147], v[20:21] op_sel_hi:[1,0,1]
	v_pk_fma_f32 v[22:23], v[46:47], v[146:147], v[22:23] op_sel_hi:[1,0,1]
	v_pk_fma_f32 v[24:25], v[48:49], v[146:147], v[24:25] op_sel_hi:[1,0,1]
	v_pk_fma_f32 v[26:27], v[50:51], v[146:147], v[26:27] op_sel_hi:[1,0,1]
	v_pk_fma_f32 v[28:29], v[52:53], v[146:147], v[28:29] op_sel_hi:[1,0,1]
	v_pk_fma_f32 v[30:31], v[54:55], v[146:147], v[30:31] op_sel_hi:[1,0,1]
	v_pk_fma_f32 v[32:33], v[56:57], v[146:147], v[32:33] op_sel_hi:[1,0,1]
	v_pk_fma_f32 v[34:35], v[58:59], v[146:147], v[34:35] op_sel_hi:[1,0,1]
	v_pk_fma_f32 v[20:21], v[66:67], v[146:147], v[20:21] op_sel:[0,1,0]
	v_pk_fma_f32 v[22:23], v[68:69], v[146:147], v[22:23] op_sel:[0,1,0]
	v_pk_fma_f32 v[24:25], v[70:71], v[146:147], v[24:25] op_sel:[0,1,0]
	v_pk_fma_f32 v[26:27], v[72:73], v[146:147], v[26:27] op_sel:[0,1,0]
	v_pk_fma_f32 v[28:29], v[74:75], v[146:147], v[28:29] op_sel:[0,1,0]
	v_pk_fma_f32 v[30:31], v[76:77], v[146:147], v[30:31] op_sel:[0,1,0]
	v_pk_fma_f32 v[32:33], v[78:79], v[146:147], v[32:33] op_sel:[0,1,0]
	v_pk_fma_f32 v[34:35], v[80:81], v[146:147], v[34:35] op_sel:[0,1,0]
	ds_write_b128 v3, v[20:23] offset:0
	ds_write_b128 v3, v[24:27] offset:128
	ds_write_b128 v3, v[28:31] offset:256
	ds_write_b128 v3, v[32:35] offset:384
	ds_read_b64 v[82:83], v4 offset:0
	ds_read_b64 v[84:85], v4 offset:512
	ds_read_b64 v[86:87], v4 offset:1024
	ds_read_b64 v[88:89], v4 offset:1536
	ds_read_b64 v[90:91], v4 offset:2048
	ds_read_b64 v[92:93], v4 offset:2560
	ds_read_b64 v[94:95], v4 offset:3072
	ds_read_b64 v[96:97], v4 offset:3584
	s_waitcnt lgkmcnt(0)
; DI void phase_peer_ffn(const Params& p) {
;     ...
;       for (int k = 0; k < 16; ++k) {
;         const float ck = __int_as_float(__builtin_amdgcn_readlane(__float_as_int(cv), lbase + k));
; #pragma unroll
;         for (int w = 0; w < 4; ++w) {
;           f2_t lo = __builtin_amdgcn_cvt_pk_f32_fp8((int)ur[k][w], false);
;           f2_t hi = __builtin_amdgcn_cvt_pk_f32_fp8((int)ur[k][w], true);
;           yacc[4 * w] = fmaf(ck, lo[0], yacc[4 * w]);
;           yacc[4 * w + 1] = fmaf(ck, lo[1], yacc[4 * w + 1]);
;           yacc[4 * w + 2] = fmaf(ck, hi[0], yacc[4 * w + 2]);
;           yacc[4 * w + 3] = fmaf(ck, hi[1], yacc[4 * w + 3]);
;         }
;       }
	v_pk_add_f32 v[82:83], v[82:83], v[84:85]
	v_pk_add_f32 v[86:87], v[86:87], v[88:89]
	v_pk_add_f32 v[90:91], v[90:91], v[92:93]
	v_pk_add_f32 v[94:95], v[94:95], v[96:97]
	v_pk_add_f32 v[82:83], v[82:83], v[86:87]
	v_pk_add_f32 v[90:91], v[90:91], v[94:95]
	s_nop 0
	v_pk_add_f32 v[82:83], v[82:83], v[90:91]
	s_nop 0
	global_store_dwordx2 v12, v[82:83], s[58:59]
	s_add_i32 s18, s18, 1
	s_add_i32 s20, s18, 1
	s_min_i32 s20, s20, 0x7f
	s_lshr_b32 s21, s20, 4
	s_and_b32 s22, s20, 15
	s_add_i32 s23, s18, 2
	s_min_i32 s23, s23, 0x7f
	s_and_b32 s24, s23, 15
	s_and_b32 s26, s18, 15
	s_lshr_b32 s27, s18, 4
	s_lshl_b32 s22, s22, 11
	s_lshl_b32 s24, s24, 11
	s_lshl_b32 s28, s21, 7
	s_lshl_b32 s26, s26, 11
	s_lshl_b32 s27, s27, 9
	v_add_u32_e32 v6, s22, v64
	v_add_u32_e32 v7, s24, v64
	v_add_u32_e32 v8, s28, v2
	v_lshl_add_u32 v10, v6, 9, v1
	v_lshl_add_u32 v9, v7, 9, v1
	v_add_u32_e32 v12, s26, v64
	v_lshl_add_u32 v12, v12, 12, v5
	v_add_u32_e32 v12, s27, v12
	s_waitcnt vmcnt(17)
	global_load_dword v116, v9, s[2:3] offset:0
	global_load_dword v117, v9, s[2:3] offset:32
	global_load_dword v118, v9, s[2:3] offset:64
	global_load_dword v119, v9, s[2:3] offset:96
	global_load_dword v120, v9, s[2:3] offset:128
	global_load_dword v121, v9, s[2:3] offset:160
	global_load_dword v122, v9, s[2:3] offset:192
	global_load_dword v123, v9, s[2:3] offset:224
	global_load_dword v124, v9, s[2:3] offset:256
	global_load_dword v125, v9, s[2:3] offset:288
	global_load_dword v126, v9, s[2:3] offset:320
	global_load_dword v127, v9, s[2:3] offset:352
	global_load_dword v128, v9, s[2:3] offset:384
	global_load_dword v129, v9, s[2:3] offset:416
	global_load_dword v130, v9, s[2:3] offset:448
	global_load_dword v131, v9, s[2:3] offset:480
	global_load_dword v132, v10, s[8:9] offset:0
	global_load_dword v133, v10, s[8:9] offset:32
	global_load_dword v134, v10, s[8:9] offset:64
	global_load_dword v135, v10, s[8:9] offset:96
	global_load_dword v136, v10, s[8:9] offset:128
	global_load_dword v137, v10, s[8:9] offset:160
	global_load_dword v138, v10, s[8:9] offset:192
	global_load_dword v139, v10, s[8:9] offset:224
	global_load_dword v140, v10, s[8:9] offset:256
	global_load_dword v141, v10, s[8:9] offset:288
	global_load_dword v142, v10, s[8:9] offset:320
	global_load_dword v143, v10, s[8:9] offset:352
	global_load_dword v144, v10, s[8:9] offset:384
	global_load_dword v145, v10, s[8:9] offset:416
	global_load_dword v146, v10, s[8:9] offset:448
	global_load_dword v147, v10, s[8:9] offset:480
	s_waitcnt vmcnt(47)
	v_cvt_pk_f32_fp8_e32 v[44:45], v180
	v_cvt_pk_f32_fp8_sdwa v[46:47], v180 src0_sel:WORD_1
	v_cvt_pk_f32_fp8_e32 v[48:49], v181
	v_cvt_pk_f32_fp8_sdwa v[50:51], v181 src0_sel:WORD_1
	v_cvt_pk_f32_fp8_e32 v[52:53], v182
	v_cvt_pk_f32_fp8_sdwa v[54:55], v182 src0_sel:WORD_1
	v_cvt_pk_f32_fp8_e32 v[56:57], v183
	v_cvt_pk_f32_fp8_sdwa v[58:59], v183 src0_sel:WORD_1
	v_cvt_pk_f32_fp8_e32 v[66:67], v184
	v_cvt_pk_f32_fp8_sdwa v[68:69], v184 src0_sel:WORD_1
	v_cvt_pk_f32_fp8_e32 v[70:71], v185
	v_cvt_pk_f32_fp8_sdwa v[72:73], v185 src0_sel:WORD_1
	v_cvt_pk_f32_fp8_e32 v[74:75], v186
	v_cvt_pk_f32_fp8_sdwa v[76:77], v186 src0_sel:WORD_1
	v_cvt_pk_f32_fp8_e32 v[78:79], v187
	v_cvt_pk_f32_fp8_sdwa v[80:81], v187 src0_sel:WORD_1
	v_lshl_add_u32 v11, v100, 10, v8
	v_lshl_add_u32 v65, v101, 10, v8
	global_load_dwordx4 v[180:183], v11, s[6:7]
	global_load_dwordx4 v[184:187], v65, s[6:7]
	v_pk_mul_f32 v[20:21], v[44:45], v[36:37] op_sel_hi:[1,0]
	v_pk_mul_f32 v[22:23], v[46:47], v[36:37] op_sel_hi:[1,0]
	v_pk_mul_f32 v[24:25], v[48:49], v[36:37] op_sel_hi:[1,0]
	v_pk_mul_f32 v[26:27], v[50:51], v[36:37] op_sel_hi:[1,0]
	v_pk_mul_f32 v[28:29], v[52:53], v[36:37] op_sel_hi:[1,0]
	v_pk_mul_f32 v[30:31], v[54:55], v[36:37] op_sel_hi:[1,0]
	v_pk_mul_f32 v[32:33], v[56:57], v[36:37] op_sel_hi:[1,0]
	v_pk_mul_f32 v[34:35], v[58:59], v[36:37] op_sel_hi:[1,0]
	v_pk_fma_f32 v[20:21], v[66:67], v[36:37], v[20:21] op_sel:[0,1,0]
	v_pk_fma_f32 v[22:23], v[68:69], v[36:37], v[22:23] op_sel:[0,1,0]
	v_pk_fma_f32 v[24:25], v[70:71], v[36:37], v[24:25] op_sel:[0,1,0]
	v_pk_fma_f32 v[26:27], v[72:73], v[36:37], v[26:27] op_sel:[0,1,0]
	v_pk_fma_f32 v[28:29], v[74:75], v[36:37], v[28:29] op_sel:[0,1,0]
	v_pk_fma_f32 v[30:31], v[76:77], v[36:37], v[30:31] op_sel:[0,1,0]
	v_pk_fma_f32 v[32:33], v[78:79], v[36:37], v[32:33] op_sel:[0,1,0]
	v_pk_fma_f32 v[34:35], v[80:81], v[36:37], v[34:35] op_sel:[0,1,0]
	s_waitcnt vmcnt(47)
	v_cvt_pk_f32_fp8_e32 v[44:45], v188
	v_cvt_pk_f32_fp8_sdwa v[46:47], v188 src0_sel:WORD_1
	v_cvt_pk_f32_fp8_e32 v[48:49], v189
	v_cvt_pk_f32_fp8_sdwa v[50:51], v189 src0_sel:WORD_1
	v_cvt_pk_f32_fp8_e32 v[52:53], v190
	v_cvt_pk_f32_fp8_sdwa v[54:55], v190 src0_sel:WORD_1
	v_cvt_pk_f32_fp8_e32 v[56:57], v191
	v_cvt_pk_f32_fp8_sdwa v[58:59], v191 src0_sel:WORD_1
	v_cvt_pk_f32_fp8_e32 v[66:67], v192
	v_cvt_pk_f32_fp8_sdwa v[68:69], v192 src0_sel:WORD_1
	v_cvt_pk_f32_fp8_e32 v[70:71], v193
	v_cvt_pk_f32_fp8_sdwa v[72:73], v193 src0_sel:WORD_1
	v_cvt_pk_f32_fp8_e32 v[74:75], v194
	v_cvt_pk_f32_fp8_sdwa v[76:77], v194 src0_sel:WORD_1
	v_cvt_pk_f32_fp8_e32 v[78:79], v195
	v_cvt_pk_f32_fp8_sdwa v[80:81], v195 src0_sel:WORD_1
	v_lshl_add_u32 v11, v102, 10, v8
	v_lshl_add_u32 v65, v103, 10, v8
	global_load_dwordx4 v[188:191], v11, s[6:7]
	global_load_dwordx4 v[192:195], v65, s[6:7]
	v_pk_fma_f32 v[20:21], v[44:45], v[38:39], v[20:21] op_sel_hi:[1,0,1]
	v_pk_fma_f32 v[22:23], v[46:47], v[38:39], v[22:23] op_sel_hi:[1,0,1]
	v_pk_fma_f32 v[24:25], v[48:49], v[38:39], v[24:25] op_sel_hi:[1,0,1]
	v_pk_fma_f32 v[26:27], v[50:51], v[38:39], v[26:27] op_sel_hi:[1,0,1]
	v_pk_fma_f32 v[28:29], v[52:53], v[38:39], v[28:29] op_sel_hi:[1,0,1]
	v_pk_fma_f32 v[30:31], v[54:55], v[38:39], v[30:31] op_sel_hi:[1,0,1]
	v_pk_fma_f32 v[32:33], v[56:57], v[38:39], v[32:33] op_sel_hi:[1,0,1]
	v_pk_fma_f32 v[34:35], v[58:59], v[38:39], v[34:35] op_sel_hi:[1,0,1]
	v_pk_fma_f32 v[20:21], v[66:67], v[38:39], v[20:21] op_sel:[0,1,0]
	v_pk_fma_f32 v[22:23], v[68:69], v[38:39], v[22:23] op_sel:[0,1,0]
	v_pk_fma_f32 v[24:25], v[70:71], v[38:39], v[24:25] op_sel:[0,1,0]
	v_pk_fma_f32 v[26:27], v[72:73], v[38:39], v[26:27] op_sel:[0,1,0]
	v_pk_fma_f32 v[28:29], v[74:75], v[38:39], v[28:29] op_sel:[0,1,0]
	v_pk_fma_f32 v[30:31], v[76:77], v[38:39], v[30:31] op_sel:[0,1,0]
	v_pk_fma_f32 v[32:33], v[78:79], v[38:39], v[32:33] op_sel:[0,1,0]
	v_pk_fma_f32 v[34:35], v[80:81], v[38:39], v[34:35] op_sel:[0,1,0]
	s_waitcnt vmcnt(47)
; DI void phase_peer_ffn(const Params& p) {
;     ...
; #pragma unroll
;       for (int k = 0; k < 16; ++k) {
;         const float ck = __int_as_float(__builtin_amdgcn_readlane(__float_as_int(cv), lbase + k));
; #pragma unroll
;         for (int w = 0; w < 4; ++w) {
;           f2_t lo = __builtin_amdgcn_cvt_pk_f32_fp8((int)ur[k][w], false);
;           f2_t hi = __builtin_amdgcn_cvt_pk_f32_fp8((int)ur[k][w], true);
;           yacc[4 * w] = fmaf(ck, lo[0], yacc[4 * w]);
;           yacc[4 * w + 1] = fmaf(ck, lo[1], yacc[4 * w + 1]);
;           yacc[4 * w + 2] = fmaf(ck, hi[0], yacc[4 * w + 2]);
;           yacc[4 * w + 3] = fmaf(ck, hi[1], yacc[4 * w + 3]);
;         }
;       }
	v_cvt_pk_f32_fp8_e32 v[44:45], v196
	v_cvt_pk_f32_fp8_sdwa v[46:47], v196 src0_sel:WORD_1
	v_cvt_pk_f32_fp8_e32 v[48:49], v197
	v_cvt_pk_f32_fp8_sdwa v[50:51], v197 src0_sel:WORD_1
	v_cvt_pk_f32_fp8_e32 v[52:53], v198
	v_cvt_pk_f32_fp8_sdwa v[54:55], v198 src0_sel:WORD_1
	v_cvt_pk_f32_fp8_e32 v[56:57], v199
	v_cvt_pk_f32_fp8_sdwa v[58:59], v199 src0_sel:WORD_1
	v_cvt_pk_f32_fp8_e32 v[66:67], v200
	v_cvt_pk_f32_fp8_sdwa v[68:69], v200 src0_sel:WORD_1
	v_cvt_pk_f32_fp8_e32 v[70:71], v201
	v_cvt_pk_f32_fp8_sdwa v[72:73], v201 src0_sel:WORD_1
	v_cvt_pk_f32_fp8_e32 v[74:75], v202
	v_cvt_pk_f32_fp8_sdwa v[76:77], v202 src0_sel:WORD_1
	v_cvt_pk_f32_fp8_e32 v[78:79], v203
	v_cvt_pk_f32_fp8_sdwa v[80:81], v203 src0_sel:WORD_1
	v_lshl_add_u32 v11, v104, 10, v8
	v_lshl_add_u32 v65, v105, 10, v8
	global_load_dwordx4 v[196:199], v11, s[6:7]
	global_load_dwordx4 v[200:203], v65, s[6:7]
	v_pk_fma_f32 v[20:21], v[44:45], v[40:41], v[20:21] op_sel_hi:[1,0,1]
	v_pk_fma_f32 v[22:23], v[46:47], v[40:41], v[22:23] op_sel_hi:[1,0,1]
	v_pk_fma_f32 v[24:25], v[48:49], v[40:41], v[24:25] op_sel_hi:[1,0,1]
	v_pk_fma_f32 v[26:27], v[50:51], v[40:41], v[26:27] op_sel_hi:[1,0,1]
	v_pk_fma_f32 v[28:29], v[52:53], v[40:41], v[28:29] op_sel_hi:[1,0,1]
	v_pk_fma_f32 v[30:31], v[54:55], v[40:41], v[30:31] op_sel_hi:[1,0,1]
	v_pk_fma_f32 v[32:33], v[56:57], v[40:41], v[32:33] op_sel_hi:[1,0,1]
	v_pk_fma_f32 v[34:35], v[58:59], v[40:41], v[34:35] op_sel_hi:[1,0,1]
	v_pk_fma_f32 v[20:21], v[66:67], v[40:41], v[20:21] op_sel:[0,1,0]
	v_pk_fma_f32 v[22:23], v[68:69], v[40:41], v[22:23] op_sel:[0,1,0]
	v_pk_fma_f32 v[24:25], v[70:71], v[40:41], v[24:25] op_sel:[0,1,0]
	v_pk_fma_f32 v[26:27], v[72:73], v[40:41], v[26:27] op_sel:[0,1,0]
	v_pk_fma_f32 v[28:29], v[74:75], v[40:41], v[28:29] op_sel:[0,1,0]
	v_pk_fma_f32 v[30:31], v[76:77], v[40:41], v[30:31] op_sel:[0,1,0]
	v_pk_fma_f32 v[32:33], v[78:79], v[40:41], v[32:33] op_sel:[0,1,0]
	v_pk_fma_f32 v[34:35], v[80:81], v[40:41], v[34:35] op_sel:[0,1,0]
	s_waitcnt vmcnt(47)
	v_cvt_pk_f32_fp8_e32 v[44:45], v204
	v_cvt_pk_f32_fp8_sdwa v[46:47], v204 src0_sel:WORD_1
	v_cvt_pk_f32_fp8_e32 v[48:49], v205
	v_cvt_pk_f32_fp8_sdwa v[50:51], v205 src0_sel:WORD_1
	v_cvt_pk_f32_fp8_e32 v[52:53], v206
	v_cvt_pk_f32_fp8_sdwa v[54:55], v206 src0_sel:WORD_1
	v_cvt_pk_f32_fp8_e32 v[56:57], v207
	v_cvt_pk_f32_fp8_sdwa v[58:59], v207 src0_sel:WORD_1
	v_cvt_pk_f32_fp8_e32 v[66:67], v208
	v_cvt_pk_f32_fp8_sdwa v[68:69], v208 src0_sel:WORD_1
	v_cvt_pk_f32_fp8_e32 v[70:71], v209
	v_cvt_pk_f32_fp8_sdwa v[72:73], v209 src0_sel:WORD_1
	v_cvt_pk_f32_fp8_e32 v[74:75], v210
	v_cvt_pk_f32_fp8_sdwa v[76:77], v210 src0_sel:WORD_1
	v_cvt_pk_f32_fp8_e32 v[78:79], v211
	v_cvt_pk_f32_fp8_sdwa v[80:81], v211 src0_sel:WORD_1
	v_lshl_add_u32 v11, v106, 10, v8
	v_lshl_add_u32 v65, v107, 10, v8
	global_load_dwordx4 v[204:207], v11, s[6:7]
	global_load_dwordx4 v[208:211], v65, s[6:7]
	v_pk_fma_f32 v[20:21], v[44:45], v[42:43], v[20:21] op_sel_hi:[1,0,1]
	v_pk_fma_f32 v[22:23], v[46:47], v[42:43], v[22:23] op_sel_hi:[1,0,1]
	v_pk_fma_f32 v[24:25], v[48:49], v[42:43], v[24:25] op_sel_hi:[1,0,1]
	v_pk_fma_f32 v[26:27], v[50:51], v[42:43], v[26:27] op_sel_hi:[1,0,1]
	v_pk_fma_f32 v[28:29], v[52:53], v[42:43], v[28:29] op_sel_hi:[1,0,1]
	v_pk_fma_f32 v[30:31], v[54:55], v[42:43], v[30:31] op_sel_hi:[1,0,1]
	v_pk_fma_f32 v[32:33], v[56:57], v[42:43], v[32:33] op_sel_hi:[1,0,1]
	v_pk_fma_f32 v[34:35], v[58:59], v[42:43], v[34:35] op_sel_hi:[1,0,1]
	v_pk_fma_f32 v[20:21], v[66:67], v[42:43], v[20:21] op_sel:[0,1,0]
	v_pk_fma_f32 v[22:23], v[68:69], v[42:43], v[22:23] op_sel:[0,1,0]
	v_pk_fma_f32 v[24:25], v[70:71], v[42:43], v[24:25] op_sel:[0,1,0]
	v_pk_fma_f32 v[26:27], v[72:73], v[42:43], v[26:27] op_sel:[0,1,0]
	v_pk_fma_f32 v[28:29], v[74:75], v[42:43], v[28:29] op_sel:[0,1,0]
	v_pk_fma_f32 v[30:31], v[76:77], v[42:43], v[30:31] op_sel:[0,1,0]
	v_pk_fma_f32 v[32:33], v[78:79], v[42:43], v[32:33] op_sel:[0,1,0]
	v_pk_fma_f32 v[34:35], v[80:81], v[42:43], v[34:35] op_sel:[0,1,0]
	s_waitcnt vmcnt(47)
	v_cvt_pk_f32_fp8_e32 v[44:45], v212
	v_cvt_pk_f32_fp8_sdwa v[46:47], v212 src0_sel:WORD_1
	v_cvt_pk_f32_fp8_e32 v[48:49], v213
	v_cvt_pk_f32_fp8_sdwa v[50:51], v213 src0_sel:WORD_1
	v_cvt_pk_f32_fp8_e32 v[52:53], v214
	v_cvt_pk_f32_fp8_sdwa v[54:55], v214 src0_sel:WORD_1
	v_cvt_pk_f32_fp8_e32 v[56:57], v215
	v_cvt_pk_f32_fp8_sdwa v[58:59], v215 src0_sel:WORD_1
	v_cvt_pk_f32_fp8_e32 v[66:67], v216
	v_cvt_pk_f32_fp8_sdwa v[68:69], v216 src0_sel:WORD_1
	v_cvt_pk_f32_fp8_e32 v[70:71], v217
	v_cvt_pk_f32_fp8_sdwa v[72:73], v217 src0_sel:WORD_1
	v_cvt_pk_f32_fp8_e32 v[74:75], v218
	v_cvt_pk_f32_fp8_sdwa v[76:77], v218 src0_sel:WORD_1
	v_cvt_pk_f32_fp8_e32 v[78:79], v219
	v_cvt_pk_f32_fp8_sdwa v[80:81], v219 src0_sel:WORD_1
	v_lshl_add_u32 v11, v108, 10, v8
	v_lshl_add_u32 v65, v109, 10, v8
	global_load_dwordx4 v[212:215], v11, s[6:7]
	global_load_dwordx4 v[216:219], v65, s[6:7]
	v_pk_fma_f32 v[20:21], v[44:45], v[244:245], v[20:21] op_sel_hi:[1,0,1]
	v_pk_fma_f32 v[22:23], v[46:47], v[244:245], v[22:23] op_sel_hi:[1,0,1]
	v_pk_fma_f32 v[24:25], v[48:49], v[244:245], v[24:25] op_sel_hi:[1,0,1]
	v_pk_fma_f32 v[26:27], v[50:51], v[244:245], v[26:27] op_sel_hi:[1,0,1]
	v_pk_fma_f32 v[28:29], v[52:53], v[244:245], v[28:29] op_sel_hi:[1,0,1]
	v_pk_fma_f32 v[30:31], v[54:55], v[244:245], v[30:31] op_sel_hi:[1,0,1]
	v_pk_fma_f32 v[32:33], v[56:57], v[244:245], v[32:33] op_sel_hi:[1,0,1]
	v_pk_fma_f32 v[34:35], v[58:59], v[244:245], v[34:35] op_sel_hi:[1,0,1]
	v_pk_fma_f32 v[20:21], v[66:67], v[244:245], v[20:21] op_sel:[0,1,0]
	v_pk_fma_f32 v[22:23], v[68:69], v[244:245], v[22:23] op_sel:[0,1,0]
	v_pk_fma_f32 v[24:25], v[70:71], v[244:245], v[24:25] op_sel:[0,1,0]
	v_pk_fma_f32 v[26:27], v[72:73], v[244:245], v[26:27] op_sel:[0,1,0]
	v_pk_fma_f32 v[28:29], v[74:75], v[244:245], v[28:29] op_sel:[0,1,0]
	v_pk_fma_f32 v[30:31], v[76:77], v[244:245], v[30:31] op_sel:[0,1,0]
	v_pk_fma_f32 v[32:33], v[78:79], v[244:245], v[32:33] op_sel:[0,1,0]
	v_pk_fma_f32 v[34:35], v[80:81], v[244:245], v[34:35] op_sel:[0,1,0]
	s_waitcnt vmcnt(47)
; DI void phase_peer_ffn(const Params& p) {
;     ...
; #pragma unroll
;       for (int k = 0; k < 16; ++k) {
;         const float ck = __int_as_float(__builtin_amdgcn_readlane(__float_as_int(cv), lbase + k));
; #pragma unroll
;         for (int w = 0; w < 4; ++w) {
;           f2_t lo = __builtin_amdgcn_cvt_pk_f32_fp8((int)ur[k][w], false);
;           f2_t hi = __builtin_amdgcn_cvt_pk_f32_fp8((int)ur[k][w], true);
;           yacc[4 * w] = fmaf(ck, lo[0], yacc[4 * w]);
;           yacc[4 * w + 1] = fmaf(ck, lo[1], yacc[4 * w + 1]);
;           yacc[4 * w + 2] = fmaf(ck, hi[0], yacc[4 * w + 2]);
;           yacc[4 * w + 3] = fmaf(ck, hi[1], yacc[4 * w + 3]);
;         }
;       }
	v_cvt_pk_f32_fp8_e32 v[44:45], v220
	v_cvt_pk_f32_fp8_sdwa v[46:47], v220 src0_sel:WORD_1
	v_cvt_pk_f32_fp8_e32 v[48:49], v221
	v_cvt_pk_f32_fp8_sdwa v[50:51], v221 src0_sel:WORD_1
	v_cvt_pk_f32_fp8_e32 v[52:53], v222
	v_cvt_pk_f32_fp8_sdwa v[54:55], v222 src0_sel:WORD_1
	v_cvt_pk_f32_fp8_e32 v[56:57], v223
	v_cvt_pk_f32_fp8_sdwa v[58:59], v223 src0_sel:WORD_1
	v_cvt_pk_f32_fp8_e32 v[66:67], v224
	v_cvt_pk_f32_fp8_sdwa v[68:69], v224 src0_sel:WORD_1
	v_cvt_pk_f32_fp8_e32 v[70:71], v225
	v_cvt_pk_f32_fp8_sdwa v[72:73], v225 src0_sel:WORD_1
	v_cvt_pk_f32_fp8_e32 v[74:75], v226
	v_cvt_pk_f32_fp8_sdwa v[76:77], v226 src0_sel:WORD_1
	v_cvt_pk_f32_fp8_e32 v[78:79], v227
	v_cvt_pk_f32_fp8_sdwa v[80:81], v227 src0_sel:WORD_1
	v_lshl_add_u32 v11, v110, 10, v8
	v_lshl_add_u32 v65, v111, 10, v8
	global_load_dwordx4 v[220:223], v11, s[6:7]
	global_load_dwordx4 v[224:227], v65, s[6:7]
	v_pk_fma_f32 v[20:21], v[44:45], v[246:247], v[20:21] op_sel_hi:[1,0,1]
	v_pk_fma_f32 v[22:23], v[46:47], v[246:247], v[22:23] op_sel_hi:[1,0,1]
	v_pk_fma_f32 v[24:25], v[48:49], v[246:247], v[24:25] op_sel_hi:[1,0,1]
	v_pk_fma_f32 v[26:27], v[50:51], v[246:247], v[26:27] op_sel_hi:[1,0,1]
	v_pk_fma_f32 v[28:29], v[52:53], v[246:247], v[28:29] op_sel_hi:[1,0,1]
	v_pk_fma_f32 v[30:31], v[54:55], v[246:247], v[30:31] op_sel_hi:[1,0,1]
	v_pk_fma_f32 v[32:33], v[56:57], v[246:247], v[32:33] op_sel_hi:[1,0,1]
	v_pk_fma_f32 v[34:35], v[58:59], v[246:247], v[34:35] op_sel_hi:[1,0,1]
	v_pk_fma_f32 v[20:21], v[66:67], v[246:247], v[20:21] op_sel:[0,1,0]
	v_pk_fma_f32 v[22:23], v[68:69], v[246:247], v[22:23] op_sel:[0,1,0]
	v_pk_fma_f32 v[24:25], v[70:71], v[246:247], v[24:25] op_sel:[0,1,0]
	v_pk_fma_f32 v[26:27], v[72:73], v[246:247], v[26:27] op_sel:[0,1,0]
	v_pk_fma_f32 v[28:29], v[74:75], v[246:247], v[28:29] op_sel:[0,1,0]
	v_pk_fma_f32 v[30:31], v[76:77], v[246:247], v[30:31] op_sel:[0,1,0]
	v_pk_fma_f32 v[32:33], v[78:79], v[246:247], v[32:33] op_sel:[0,1,0]
	v_pk_fma_f32 v[34:35], v[80:81], v[246:247], v[34:35] op_sel:[0,1,0]
	s_waitcnt vmcnt(47)
	v_cvt_pk_f32_fp8_e32 v[44:45], v228
	v_cvt_pk_f32_fp8_sdwa v[46:47], v228 src0_sel:WORD_1
	v_cvt_pk_f32_fp8_e32 v[48:49], v229
	v_cvt_pk_f32_fp8_sdwa v[50:51], v229 src0_sel:WORD_1
	v_cvt_pk_f32_fp8_e32 v[52:53], v230
	v_cvt_pk_f32_fp8_sdwa v[54:55], v230 src0_sel:WORD_1
	v_cvt_pk_f32_fp8_e32 v[56:57], v231
	v_cvt_pk_f32_fp8_sdwa v[58:59], v231 src0_sel:WORD_1
	v_cvt_pk_f32_fp8_e32 v[66:67], v232
	v_cvt_pk_f32_fp8_sdwa v[68:69], v232 src0_sel:WORD_1
	v_cvt_pk_f32_fp8_e32 v[70:71], v233
	v_cvt_pk_f32_fp8_sdwa v[72:73], v233 src0_sel:WORD_1
	v_cvt_pk_f32_fp8_e32 v[74:75], v234
	v_cvt_pk_f32_fp8_sdwa v[76:77], v234 src0_sel:WORD_1
	v_cvt_pk_f32_fp8_e32 v[78:79], v235
	v_cvt_pk_f32_fp8_sdwa v[80:81], v235 src0_sel:WORD_1
	v_lshl_add_u32 v11, v112, 10, v8
	v_lshl_add_u32 v65, v113, 10, v8
	global_load_dwordx4 v[228:231], v11, s[6:7]
	global_load_dwordx4 v[232:235], v65, s[6:7]
	v_pk_fma_f32 v[20:21], v[44:45], v[248:249], v[20:21] op_sel_hi:[1,0,1]
	v_pk_fma_f32 v[22:23], v[46:47], v[248:249], v[22:23] op_sel_hi:[1,0,1]
	v_pk_fma_f32 v[24:25], v[48:49], v[248:249], v[24:25] op_sel_hi:[1,0,1]
	v_pk_fma_f32 v[26:27], v[50:51], v[248:249], v[26:27] op_sel_hi:[1,0,1]
	v_pk_fma_f32 v[28:29], v[52:53], v[248:249], v[28:29] op_sel_hi:[1,0,1]
	v_pk_fma_f32 v[30:31], v[54:55], v[248:249], v[30:31] op_sel_hi:[1,0,1]
	v_pk_fma_f32 v[32:33], v[56:57], v[248:249], v[32:33] op_sel_hi:[1,0,1]
	v_pk_fma_f32 v[34:35], v[58:59], v[248:249], v[34:35] op_sel_hi:[1,0,1]
	v_pk_fma_f32 v[20:21], v[66:67], v[248:249], v[20:21] op_sel:[0,1,0]
	v_pk_fma_f32 v[22:23], v[68:69], v[248:249], v[22:23] op_sel:[0,1,0]
	v_pk_fma_f32 v[24:25], v[70:71], v[248:249], v[24:25] op_sel:[0,1,0]
	v_pk_fma_f32 v[26:27], v[72:73], v[248:249], v[26:27] op_sel:[0,1,0]
	v_pk_fma_f32 v[28:29], v[74:75], v[248:249], v[28:29] op_sel:[0,1,0]
	v_pk_fma_f32 v[30:31], v[76:77], v[248:249], v[30:31] op_sel:[0,1,0]
	v_pk_fma_f32 v[32:33], v[78:79], v[248:249], v[32:33] op_sel:[0,1,0]
	v_pk_fma_f32 v[34:35], v[80:81], v[248:249], v[34:35] op_sel:[0,1,0]
	s_waitcnt vmcnt(47)
	v_cvt_pk_f32_fp8_e32 v[44:45], v236
	v_cvt_pk_f32_fp8_sdwa v[46:47], v236 src0_sel:WORD_1
	v_cvt_pk_f32_fp8_e32 v[48:49], v237
	v_cvt_pk_f32_fp8_sdwa v[50:51], v237 src0_sel:WORD_1
	v_cvt_pk_f32_fp8_e32 v[52:53], v238
	v_cvt_pk_f32_fp8_sdwa v[54:55], v238 src0_sel:WORD_1
	v_cvt_pk_f32_fp8_e32 v[56:57], v239
	v_cvt_pk_f32_fp8_sdwa v[58:59], v239 src0_sel:WORD_1
	v_cvt_pk_f32_fp8_e32 v[66:67], v240
	v_cvt_pk_f32_fp8_sdwa v[68:69], v240 src0_sel:WORD_1
	v_cvt_pk_f32_fp8_e32 v[70:71], v241
	v_cvt_pk_f32_fp8_sdwa v[72:73], v241 src0_sel:WORD_1
	v_cvt_pk_f32_fp8_e32 v[74:75], v242
	v_cvt_pk_f32_fp8_sdwa v[76:77], v242 src0_sel:WORD_1
	v_cvt_pk_f32_fp8_e32 v[78:79], v243
	v_cvt_pk_f32_fp8_sdwa v[80:81], v243 src0_sel:WORD_1
	v_lshl_add_u32 v11, v114, 10, v8
	v_lshl_add_u32 v65, v115, 10, v8
	global_load_dwordx4 v[236:239], v11, s[6:7]
	global_load_dwordx4 v[240:243], v65, s[6:7]
	v_pk_fma_f32 v[20:21], v[44:45], v[250:251], v[20:21] op_sel_hi:[1,0,1]
	v_pk_fma_f32 v[22:23], v[46:47], v[250:251], v[22:23] op_sel_hi:[1,0,1]
	v_pk_fma_f32 v[24:25], v[48:49], v[250:251], v[24:25] op_sel_hi:[1,0,1]
	v_pk_fma_f32 v[26:27], v[50:51], v[250:251], v[26:27] op_sel_hi:[1,0,1]
	v_pk_fma_f32 v[28:29], v[52:53], v[250:251], v[28:29] op_sel_hi:[1,0,1]
	v_pk_fma_f32 v[30:31], v[54:55], v[250:251], v[30:31] op_sel_hi:[1,0,1]
	v_pk_fma_f32 v[32:33], v[56:57], v[250:251], v[32:33] op_sel_hi:[1,0,1]
	v_pk_fma_f32 v[34:35], v[58:59], v[250:251], v[34:35] op_sel_hi:[1,0,1]
	v_pk_fma_f32 v[20:21], v[66:67], v[250:251], v[20:21] op_sel:[0,1,0]
	v_pk_fma_f32 v[22:23], v[68:69], v[250:251], v[22:23] op_sel:[0,1,0]
	v_pk_fma_f32 v[24:25], v[70:71], v[250:251], v[24:25] op_sel:[0,1,0]
	v_pk_fma_f32 v[26:27], v[72:73], v[250:251], v[26:27] op_sel:[0,1,0]
	v_pk_fma_f32 v[28:29], v[74:75], v[250:251], v[28:29] op_sel:[0,1,0]
	v_pk_fma_f32 v[30:31], v[76:77], v[250:251], v[30:31] op_sel:[0,1,0]
	v_pk_fma_f32 v[32:33], v[78:79], v[250:251], v[32:33] op_sel:[0,1,0]
	v_pk_fma_f32 v[34:35], v[80:81], v[250:251], v[34:35] op_sel:[0,1,0]
	ds_write_b128 v3, v[20:23] offset:0
	ds_write_b128 v3, v[24:27] offset:128
	ds_write_b128 v3, v[28:31] offset:256
	ds_write_b128 v3, v[32:35] offset:384
	ds_read_b64 v[82:83], v4 offset:0
	ds_read_b64 v[84:85], v4 offset:512
	ds_read_b64 v[86:87], v4 offset:1024
	ds_read_b64 v[88:89], v4 offset:1536
	ds_read_b64 v[90:91], v4 offset:2048
	ds_read_b64 v[92:93], v4 offset:2560
	ds_read_b64 v[94:95], v4 offset:3072
	ds_read_b64 v[96:97], v4 offset:3584
	s_waitcnt lgkmcnt(0)
	v_pk_add_f32 v[82:83], v[82:83], v[84:85]
	v_pk_add_f32 v[86:87], v[86:87], v[88:89]
	v_pk_add_f32 v[90:91], v[90:91], v[92:93]
	v_pk_add_f32 v[94:95], v[94:95], v[96:97]
	v_pk_add_f32 v[82:83], v[82:83], v[86:87]
	v_pk_add_f32 v[90:91], v[90:91], v[94:95]
	s_nop 0
	v_pk_add_f32 v[82:83], v[82:83], v[90:91]
	s_nop 0
	global_store_dwordx2 v12, v[82:83], s[58:59]
	s_add_i32 s18, s18, 1
	s_cmpk_lt_u32 s18, 0x80
	s_cbranch_scc1 .Lpf_loop
; DI void phase_peer_ffn(const Params& p) {
;     ...
;     const float* xr = h + (size_t)tok * 1024 + lane * 16;
;     float v[16];
; #pragma unroll
;     for (int c = 0; c < 4; ++c) {
;       f32x4 t = *reinterpret_cast<const f32x4*>(xr + c * 4);
; #pragma unroll
;       for (int k = 0; k < 4; ++k) v[4 * c + k] = ALPHA * t[k] + yacc[4 * c + k];
;     }
;     float s = 0.f;
; #pragma unroll
;     for (int i = 0; i < 16; ++i) s += v[i];
;     const float mean = wave_sum(s) * (1.f / 1024.f);
;     float q = 0.f;
; #pragma unroll
;     for (int i = 0; i < 16; ++i) { float d = v[i] - mean; q += d * d; }
;     const float rstd = rsqrtf(wave_sum(q) * (1.f / 1024.f) + 1e-5f);
;     float* orow = p.out + (size_t)tok * 1024 + lane * 16;
; #pragma unroll
;     for (int c = 0; c < 4; ++c) {
;       f32x4 gg = *reinterpret_cast<const f32x4*>(p.ln_ffn_g + lane * 16 + c * 4);
;       f32x4 bb = *reinterpret_cast<const f32x4*>(p.ln_ffn_b + lane * 16 + c * 4);
;       f32x4 o;
; #pragma unroll
;       for (int k = 0; k < 4; ++k) o[k] = (v[4 * c + k] - mean) * rstd * gg[k] + bb[k];
;       *reinterpret_cast<f32x4*>(orow + c * 4) = o;
;     }
	s_waitcnt vmcnt(0) lgkmcnt(0)
	v_lshlrev_b32_e32 v1, 6, v0
	global_load_dwordx4 v[100:103], v1, s[54:55]
	global_load_dwordx4 v[104:107], v1, s[54:55] offset:16
	global_load_dwordx4 v[108:111], v1, s[54:55] offset:32
	global_load_dwordx4 v[112:115], v1, s[54:55] offset:48
	global_load_dwordx4 v[116:119], v1, s[56:57]
	global_load_dwordx4 v[120:123], v1, s[56:57] offset:16
	global_load_dwordx4 v[124:127], v1, s[56:57] offset:32
	global_load_dwordx4 v[128:131], v1, s[56:57] offset:48
	s_mov_b32 s4, 0x3f9837f0
	s_mov_b32 s5, 0
	v_mov_b32_e32 v3, 0x3727c5ac
	s_mov_b32 s18, 0
	s_mov_b32 s19, 0x800
	v_add_u32_e32 v2, s18, v64
	v_lshl_add_u32 v2, v2, 12, v1
	global_load_dwordx4 v[20:23], v2, s[58:59] sc1
	global_load_dwordx4 v[24:27], v2, s[58:59] offset:16 sc1
	global_load_dwordx4 v[28:31], v2, s[58:59] offset:32 sc1
	global_load_dwordx4 v[32:35], v2, s[58:59] offset:48 sc1
	global_load_dwordx4 v[36:39], v2, s[82:83]
	global_load_dwordx4 v[40:43], v2, s[82:83] offset:16
	global_load_dwordx4 v[44:47], v2, s[82:83] offset:32
	global_load_dwordx4 v[48:51], v2, s[82:83] offset:48
.Lpf_ln:
	v_add_u32_e32 v2, s19, v64
	v_lshl_add_u32 v2, v2, 12, v1
	global_load_dwordx4 v[180:183], v2, s[58:59] sc1
	global_load_dwordx4 v[184:187], v2, s[58:59] offset:16 sc1
	global_load_dwordx4 v[188:191], v2, s[58:59] offset:32 sc1
	global_load_dwordx4 v[192:195], v2, s[58:59] offset:48 sc1
	global_load_dwordx4 v[196:199], v2, s[82:83]
	global_load_dwordx4 v[200:203], v2, s[82:83] offset:16
	global_load_dwordx4 v[204:207], v2, s[82:83] offset:32
	global_load_dwordx4 v[208:211], v2, s[82:83] offset:48
	s_waitcnt vmcnt(8)
	v_pk_fma_f32 v[66:67], v[36:37], s[4:5], v[20:21] op_sel_hi:[1,0,1]
	v_pk_fma_f32 v[68:69], v[38:39], s[4:5], v[22:23] op_sel_hi:[1,0,1]
	v_pk_fma_f32 v[70:71], v[40:41], s[4:5], v[24:25] op_sel_hi:[1,0,1]
	v_pk_fma_f32 v[72:73], v[42:43], s[4:5], v[26:27] op_sel_hi:[1,0,1]
	v_pk_fma_f32 v[74:75], v[44:45], s[4:5], v[28:29] op_sel_hi:[1,0,1]
	v_pk_fma_f32 v[76:77], v[46:47], s[4:5], v[30:31] op_sel_hi:[1,0,1]
	v_pk_fma_f32 v[78:79], v[48:49], s[4:5], v[32:33] op_sel_hi:[1,0,1]
	v_pk_fma_f32 v[80:81], v[50:51], s[4:5], v[34:35] op_sel_hi:[1,0,1]
	v_pk_add_f32 v[82:83], v[66:67], v[68:69]
	v_pk_add_f32 v[84:85], v[70:71], v[72:73]
	v_pk_add_f32 v[86:87], v[74:75], v[76:77]
	v_pk_add_f32 v[88:89], v[78:79], v[80:81]
	v_pk_add_f32 v[82:83], v[82:83], v[84:85]
	v_pk_add_f32 v[86:87], v[86:87], v[88:89]
	s_nop 0
	v_pk_add_f32 v[82:83], v[82:83], v[86:87]
	s_nop 0
	v_add_f32_e32 v82, v82, v83
	s_nop 1
	v_add_f32_dpp v83, v82, v82 quad_perm:[1,0,3,2] row_mask:0xf bank_mask:0xf
	s_nop 1
	v_add_f32_dpp v82, v83, v83 quad_perm:[2,3,0,1] row_mask:0xf bank_mask:0xf
	s_nop 1
	v_add_f32_dpp v83, v82, v82 row_half_mirror row_mask:0xf bank_mask:0xf
	s_nop 1
	v_add_f32_dpp v82, v83, v83 row_mirror row_mask:0xf bank_mask:0xf
	s_nop 1
	v_readlane_b32 s20, v82, 0
	v_readlane_b32 s21, v82, 16
	v_readlane_b32 s22, v82, 32
	v_readlane_b32 s23, v82, 48
	s_nop 1
	v_mov_b32_e32 v83, s20
	v_add_f32_e32 v83, s21, v83
	v_add_f32_e32 v83, s22, v83
	v_add_f32_e32 v83, s23, v83
	v_mul_f32_e32 v84, 0x3a800000, v83
	v_mov_b32_e32 v85, v84
	v_pk_add_f32 v[66:67], v[66:67], v[84:85] neg_lo:[0,1] neg_hi:[0,1]
	v_pk_add_f32 v[68:69], v[68:69], v[84:85] neg_lo:[0,1] neg_hi:[0,1]
	v_pk_add_f32 v[70:71], v[70:71], v[84:85] neg_lo:[0,1] neg_hi:[0,1]
	v_pk_add_f32 v[72:73], v[72:73], v[84:85] neg_lo:[0,1] neg_hi:[0,1]
	v_pk_add_f32 v[74:75], v[74:75], v[84:85] neg_lo:[0,1] neg_hi:[0,1]
	v_pk_add_f32 v[76:77], v[76:77], v[84:85] neg_lo:[0,1] neg_hi:[0,1]
	v_pk_add_f32 v[78:79], v[78:79], v[84:85] neg_lo:[0,1] neg_hi:[0,1]
	v_pk_add_f32 v[80:81], v[80:81], v[84:85] neg_lo:[0,1] neg_hi:[0,1]
	v_pk_mul_f32 v[82:83], v[66:67], v[66:67]
	v_pk_mul_f32 v[86:87], v[68:69], v[68:69]
	v_pk_fma_f32 v[82:83], v[70:71], v[70:71], v[82:83]
	v_pk_fma_f32 v[86:87], v[72:73], v[72:73], v[86:87]
	v_pk_fma_f32 v[82:83], v[74:75], v[74:75], v[82:83]
	v_pk_fma_f32 v[86:87], v[76:77], v[76:77], v[86:87]
	v_pk_fma_f32 v[82:83], v[78:79], v[78:79], v[82:83]
	v_pk_fma_f32 v[86:87], v[80:81], v[80:81], v[86:87]
	v_pk_add_f32 v[82:83], v[82:83], v[86:87]
	s_nop 0
	v_add_f32_e32 v82, v82, v83
	s_nop 1
	v_add_f32_dpp v83, v82, v82 quad_perm:[1,0,3,2] row_mask:0xf bank_mask:0xf
	s_nop 1
	v_add_f32_dpp v82, v83, v83 quad_perm:[2,3,0,1] row_mask:0xf bank_mask:0xf
	s_nop 1
	v_add_f32_dpp v83, v82, v82 row_half_mirror row_mask:0xf bank_mask:0xf
	s_nop 1
	v_add_f32_dpp v82, v83, v83 row_mirror row_mask:0xf bank_mask:0xf
	s_nop 1
	v_readlane_b32 s20, v82, 0
	v_readlane_b32 s21, v82, 16
	v_readlane_b32 s22, v82, 32
	v_readlane_b32 s23, v82, 48
	s_nop 1
	v_mov_b32_e32 v83, s20
	v_add_f32_e32 v83, s21, v83
	v_add_f32_e32 v83, s22, v83
	v_add_f32_e32 v83, s23, v83
	v_fmamk_f32 v83, v83, 0x3a800000, v3
	v_rsq_f32_e32 v83, v83
	s_nop 1
	v_mov_b32_e32 v82, v83
	s_nop 0
	v_pk_mul_f32 v[66:67], v[66:67], v[82:83]
	v_pk_mul_f32 v[68:69], v[68:69], v[82:83]
	v_pk_mul_f32 v[70:71], v[70:71], v[82:83]
	v_pk_mul_f32 v[72:73], v[72:73], v[82:83]
	v_pk_mul_f32 v[74:75], v[74:75], v[82:83]
	v_pk_mul_f32 v[76:77], v[76:77], v[82:83]
	v_pk_mul_f32 v[78:79], v[78:79], v[82:83]
	v_pk_mul_f32 v[80:81], v[80:81], v[82:83]
	v_pk_fma_f32 v[66:67], v[66:67], v[100:101], v[116:117]
	v_pk_fma_f32 v[68:69], v[68:69], v[102:103], v[118:119]
	v_pk_fma_f32 v[70:71], v[70:71], v[104:105], v[120:121]
	v_pk_fma_f32 v[72:73], v[72:73], v[106:107], v[122:123]
	v_pk_fma_f32 v[74:75], v[74:75], v[108:109], v[124:125]
	v_pk_fma_f32 v[76:77], v[76:77], v[110:111], v[126:127]
	v_pk_fma_f32 v[78:79], v[78:79], v[112:113], v[128:129]
	v_pk_fma_f32 v[80:81], v[80:81], v[114:115], v[130:131]
	v_add_u32_e32 v2, s18, v64
	v_lshl_add_u32 v2, v2, 12, v1
	global_store_dwordx4 v2, v[66:69], s[58:59]
	global_store_dwordx4 v2, v[70:73], s[58:59] offset:16
	global_store_dwordx4 v2, v[74:77], s[58:59] offset:32
	global_store_dwordx4 v2, v[78:81], s[58:59] offset:48
	s_add_i32 s18, s18, 0x1000
	s_min_u32 s26, s18, 0x7800
	v_add_u32_e32 v2, s26, v64
	v_lshl_add_u32 v2, v2, 12, v1
	global_load_dwordx4 v[20:23], v2, s[58:59] sc1
	global_load_dwordx4 v[24:27], v2, s[58:59] offset:16 sc1
	global_load_dwordx4 v[28:31], v2, s[58:59] offset:32 sc1
	global_load_dwordx4 v[32:35], v2, s[58:59] offset:48 sc1
	global_load_dwordx4 v[36:39], v2, s[82:83]
	global_load_dwordx4 v[40:43], v2, s[82:83] offset:16
	global_load_dwordx4 v[44:47], v2, s[82:83] offset:32
	global_load_dwordx4 v[48:51], v2, s[82:83] offset:48
	s_waitcnt vmcnt(12)
; DI void phase_peer_ffn(const Params& p) {
;     ...
;     float s = 0.f;
; #pragma unroll
;     for (int i = 0; i < 16; ++i) s += v[i];
;     const float mean = wave_sum(s) * (1.f / 1024.f);
;     float q = 0.f;
; #pragma unroll
;     for (int i = 0; i < 16; ++i) { float d = v[i] - mean; q += d * d; }
;     const float rstd = rsqrtf(wave_sum(q) * (1.f / 1024.f) + 1e-5f);
;     float* orow = p.out + (size_t)tok * 1024 + lane * 16;
; #pragma unroll
;     for (int c = 0; c < 4; ++c) {
;       f32x4 gg = *reinterpret_cast<const f32x4*>(p.ln_ffn_g + lane * 16 + c * 4);
;       f32x4 bb = *reinterpret_cast<const f32x4*>(p.ln_ffn_b + lane * 16 + c * 4);
;       f32x4 o;
; #pragma unroll
;       for (int k = 0; k < 4; ++k) o[k] = (v[4 * c + k] - mean) * rstd * gg[k] + bb[k];
;       *reinterpret_cast<f32x4*>(orow + c * 4) = o;
;     }
	v_pk_fma_f32 v[66:67], v[196:197], s[4:5], v[180:181] op_sel_hi:[1,0,1]
	v_pk_fma_f32 v[68:69], v[198:199], s[4:5], v[182:183] op_sel_hi:[1,0,1]
	v_pk_fma_f32 v[70:71], v[200:201], s[4:5], v[184:185] op_sel_hi:[1,0,1]
	v_pk_fma_f32 v[72:73], v[202:203], s[4:5], v[186:187] op_sel_hi:[1,0,1]
	v_pk_fma_f32 v[74:75], v[204:205], s[4:5], v[188:189] op_sel_hi:[1,0,1]
	v_pk_fma_f32 v[76:77], v[206:207], s[4:5], v[190:191] op_sel_hi:[1,0,1]
	v_pk_fma_f32 v[78:79], v[208:209], s[4:5], v[192:193] op_sel_hi:[1,0,1]
	v_pk_fma_f32 v[80:81], v[210:211], s[4:5], v[194:195] op_sel_hi:[1,0,1]
	v_pk_add_f32 v[82:83], v[66:67], v[68:69]
	v_pk_add_f32 v[84:85], v[70:71], v[72:73]
	v_pk_add_f32 v[86:87], v[74:75], v[76:77]
	v_pk_add_f32 v[88:89], v[78:79], v[80:81]
	v_pk_add_f32 v[82:83], v[82:83], v[84:85]
	v_pk_add_f32 v[86:87], v[86:87], v[88:89]
	s_nop 0
	v_pk_add_f32 v[82:83], v[82:83], v[86:87]
	s_nop 0
	v_add_f32_e32 v82, v82, v83
	s_nop 1
	v_add_f32_dpp v83, v82, v82 quad_perm:[1,0,3,2] row_mask:0xf bank_mask:0xf
	s_nop 1
	v_add_f32_dpp v82, v83, v83 quad_perm:[2,3,0,1] row_mask:0xf bank_mask:0xf
	s_nop 1
	v_add_f32_dpp v83, v82, v82 row_half_mirror row_mask:0xf bank_mask:0xf
	s_nop 1
	v_add_f32_dpp v82, v83, v83 row_mirror row_mask:0xf bank_mask:0xf
	s_nop 1
	v_readlane_b32 s20, v82, 0
	v_readlane_b32 s21, v82, 16
	v_readlane_b32 s22, v82, 32
	v_readlane_b32 s23, v82, 48
	s_nop 1
	v_mov_b32_e32 v83, s20
	v_add_f32_e32 v83, s21, v83
	v_add_f32_e32 v83, s22, v83
	v_add_f32_e32 v83, s23, v83
	v_mul_f32_e32 v84, 0x3a800000, v83
	v_mov_b32_e32 v85, v84
	v_pk_add_f32 v[66:67], v[66:67], v[84:85] neg_lo:[0,1] neg_hi:[0,1]
	v_pk_add_f32 v[68:69], v[68:69], v[84:85] neg_lo:[0,1] neg_hi:[0,1]
	v_pk_add_f32 v[70:71], v[70:71], v[84:85] neg_lo:[0,1] neg_hi:[0,1]
	v_pk_add_f32 v[72:73], v[72:73], v[84:85] neg_lo:[0,1] neg_hi:[0,1]
	v_pk_add_f32 v[74:75], v[74:75], v[84:85] neg_lo:[0,1] neg_hi:[0,1]
	v_pk_add_f32 v[76:77], v[76:77], v[84:85] neg_lo:[0,1] neg_hi:[0,1]
	v_pk_add_f32 v[78:79], v[78:79], v[84:85] neg_lo:[0,1] neg_hi:[0,1]
	v_pk_add_f32 v[80:81], v[80:81], v[84:85] neg_lo:[0,1] neg_hi:[0,1]
	v_pk_mul_f32 v[82:83], v[66:67], v[66:67]
	v_pk_mul_f32 v[86:87], v[68:69], v[68:69]
	v_pk_fma_f32 v[82:83], v[70:71], v[70:71], v[82:83]
	v_pk_fma_f32 v[86:87], v[72:73], v[72:73], v[86:87]
	v_pk_fma_f32 v[82:83], v[74:75], v[74:75], v[82:83]
	v_pk_fma_f32 v[86:87], v[76:77], v[76:77], v[86:87]
	v_pk_fma_f32 v[82:83], v[78:79], v[78:79], v[82:83]
	v_pk_fma_f32 v[86:87], v[80:81], v[80:81], v[86:87]
	v_pk_add_f32 v[82:83], v[82:83], v[86:87]
	s_nop 0
	v_add_f32_e32 v82, v82, v83
	s_nop 1
	v_add_f32_dpp v83, v82, v82 quad_perm:[1,0,3,2] row_mask:0xf bank_mask:0xf
	s_nop 1
	v_add_f32_dpp v82, v83, v83 quad_perm:[2,3,0,1] row_mask:0xf bank_mask:0xf
	s_nop 1
	v_add_f32_dpp v83, v82, v82 row_half_mirror row_mask:0xf bank_mask:0xf
	s_nop 1
	v_add_f32_dpp v82, v83, v83 row_mirror row_mask:0xf bank_mask:0xf
	s_nop 1
	v_readlane_b32 s20, v82, 0
	v_readlane_b32 s21, v82, 16
	v_readlane_b32 s22, v82, 32
	v_readlane_b32 s23, v82, 48
	s_nop 1
	v_mov_b32_e32 v83, s20
	v_add_f32_e32 v83, s21, v83
	v_add_f32_e32 v83, s22, v83
	v_add_f32_e32 v83, s23, v83
	v_fmamk_f32 v83, v83, 0x3a800000, v3
	v_rsq_f32_e32 v83, v83
	s_nop 1
	v_mov_b32_e32 v82, v83
	s_nop 0
	v_pk_mul_f32 v[66:67], v[66:67], v[82:83]
	v_pk_mul_f32 v[68:69], v[68:69], v[82:83]
	v_pk_mul_f32 v[70:71], v[70:71], v[82:83]
	v_pk_mul_f32 v[72:73], v[72:73], v[82:83]
	v_pk_mul_f32 v[74:75], v[74:75], v[82:83]
	v_pk_mul_f32 v[76:77], v[76:77], v[82:83]
	v_pk_mul_f32 v[78:79], v[78:79], v[82:83]
	v_pk_mul_f32 v[80:81], v[80:81], v[82:83]
	v_pk_fma_f32 v[66:67], v[66:67], v[100:101], v[116:117]
	v_pk_fma_f32 v[68:69], v[68:69], v[102:103], v[118:119]
	v_pk_fma_f32 v[70:71], v[70:71], v[104:105], v[120:121]
	v_pk_fma_f32 v[72:73], v[72:73], v[106:107], v[122:123]
	v_pk_fma_f32 v[74:75], v[74:75], v[108:109], v[124:125]
	v_pk_fma_f32 v[76:77], v[76:77], v[110:111], v[126:127]
	v_pk_fma_f32 v[78:79], v[78:79], v[112:113], v[128:129]
	v_pk_fma_f32 v[80:81], v[80:81], v[114:115], v[130:131]
	v_add_u32_e32 v2, s19, v64
	v_lshl_add_u32 v2, v2, 12, v1
	global_store_dwordx4 v2, v[66:69], s[58:59]
	global_store_dwordx4 v2, v[70:73], s[58:59] offset:16
	global_store_dwordx4 v2, v[74:77], s[58:59] offset:32
	global_store_dwordx4 v2, v[78:81], s[58:59] offset:48
	s_add_i32 s19, s19, 0x1000
	s_cmpk_lt_u32 s18, 0x8000
	s_cbranch_scc1 .Lpf_ln
